# prologue weight conversion: workgroup-contiguous item order (40 consecutive items per WG) instead of grid-strided
# speedup vs baseline: 1.0039x; 1.0039x over previous
.LBB0_24:
	v_mov_b32_e32 v2, v179
	s_barrier
	s_lshl_b32 s1, s2, 3
	v_readfirstlane_b32 s0, v2
	s_ashr_i32 s0, s0, 6
	v_writelane_b32 v249, s1, 24
	s_add_i32 s8, s0, s1
	s_mov_b32 s101, s8
	s_lshl_b32 s38, s30, 3
	v_writelane_b32 v249, s70, 25
	s_cmpk_gt_i32 s8, 0x2a7f
	s_nop 0
	v_writelane_b32 v249, s71, 26
	s_cbranch_scc1 .LBB0_44
	v_bfe_u32 v1, v2, 5, 1
	v_and_b32_e32 v20, 31, v2
	v_bfe_u32 v23, v2, 3, 3
	v_lshlrev_b32_e32 v2, 3, v2
	v_and_b32_e32 v28, 56, v2
	s_lshl_b32 s1, s0, 14
	v_mov_b32_e32 v3, 0
	v_lshlrev_b32_e32 v2, 1, v28
	s_add_i32 s1, s1, 0
	v_lshlrev_b32_e32 v18, 2, v20
	v_mul_u32_u24_e32 v4, 0x84, v1
	v_lshl_add_u64 v[10:11], s[28:29], 0, v[2:3]
	s_mov_b64 s[4:5], 0x2900000
	v_add3_u32 v22, s1, v18, v4
	v_mul_u32_u24_e32 v6, 0x84, v28
	v_lshl_add_u64 v[4:5], v[10:11], 0, s[4:5]
	v_lshlrev_b32_e32 v2, 2, v23
	s_mov_b64 s[4:5], 0x1c00000
	v_add3_u32 v24, s1, v6, v2
	v_lshl_add_u64 v[6:7], v[10:11], 0, s[4:5]
	s_mov_b64 s[4:5], 0x1400000
	v_lshl_add_u64 v[8:9], v[10:11], 0, s[4:5]
	s_mov_b64 s[4:5], 0xe00000
	v_readlane_b32 s40, v249, 0
	v_lshl_add_u64 v[10:11], v[10:11], 0, s[4:5]
	v_mov_b32_e32 v19, v3
	v_readlane_b32 s41, v249, 1
	v_readlane_b32 s42, v249, 2
	v_readlane_b32 s43, v249, 3
	v_readlane_b32 s44, v249, 4
	v_readlane_b32 s45, v249, 5
	v_readlane_b32 s46, v249, 6
	v_readlane_b32 s47, v249, 7
	s_lshl_b32 s1, s2, 4
	s_lshl_b32 s4, s0, 1
	v_lshl_add_u64 v[12:13], s[42:43], 0, v[18:19]
	v_readlane_b32 s40, v249, 8
	s_add_i32 s1, s1, s4
	v_readlane_b32 s41, v249, 9
	v_readlane_b32 s42, v249, 10
	v_readlane_b32 s43, v249, 11
	v_readlane_b32 s44, v249, 12
	v_readlane_b32 s45, v249, 13
	v_readlane_b32 s46, v249, 14
	v_readlane_b32 s47, v249, 15
	v_readlane_b32 s48, v249, 16
	v_readlane_b32 s49, v249, 17
	v_readlane_b32 s50, v249, 18
	v_readlane_b32 s51, v249, 19
	v_readlane_b32 s52, v249, 20
	v_readlane_b32 s53, v249, 21
	v_readlane_b32 s54, v249, 22
	v_readlane_b32 s55, v249, 23
	s_add_i32 s9, s1, 0x7fffd000
	s_lshl_b32 s1, s2, 8
	s_lshl_b32 s0, s0, 5
	v_or_b32_e32 v25, 8, v23
	v_or_b32_e32 v26, 16, v23
	v_or_b32_e32 v27, 24, v23
	v_lshl_add_u64 v[14:15], s[52:53], 0, v[18:19]
	v_lshl_add_u64 v[16:17], s[84:85], 0, v[18:19]
	v_lshl_add_u64 v[18:19], s[80:81], 0, v[18:19]
	s_lshl_b32 s14, s30, 4
	s_add_i32 s15, s1, s0
	s_lshl_b32 s16, s30, 8
	s_movk_i32 s17, 0x7000
	s_mov_b32 s18, 0xf000
	s_mov_b32 s19, 0x16000
	s_mov_b32 s20, 0x1e000
	s_mov_b32 s21, 0x25000
	s_mov_b32 s23, 0x2d000
	s_mov_b32 s33, 0x34000
	s_mov_b32 s34, 0x3c000
	s_mov_b32 s35, 0x43000
	s_mov_b32 s36, 0x4b000
	s_mov_b32 s37, 0x52000
	s_mov_b32 s39, 0x5a000
	s_mov_b32 s40, 0x61000
	s_mov_b32 s41, 0x69000
	s_mov_b32 s42, 0x70000
	s_mov_b32 s43, 0x78000
	s_mov_b32 s44, 0x7f000
	s_mov_b32 s45, 0x87000
	s_mov_b32 s46, 0x8e000
	s_mov_b32 s47, 0x96000
	s_mov_b32 s48, 0x9d000
	s_mov_b32 s49, 0xa5000
	s_mov_b32 s50, 0xac000
	v_lshlrev_b32_e32 v2, 2, v20
	v_lshlrev_b32_e32 v20, 1, v28
	v_add_u32_e32 v28, 0x400, v22
	v_add_u32_e32 v29, 0x800, v22
	v_add_u32_e32 v30, 0xc00, v22
	v_add_u32_e32 v31, 0x1000, v22
	v_add_u32_e32 v32, 0x1400, v22
	v_add_u32_e32 v33, 0x1800, v22
	v_add_u32_e32 v34, 0x1c00, v22
	s_mov_b32 s51, 0xb4000
	s_mov_b32 s52, 0xbb000
	s_mov_b32 s53, 0xc3000
	s_mov_b32 s54, 0xca000
	s_mov_b32 s55, 0xd2000
	s_mov_b32 s56, 0xd9000
	s_mov_b32 s57, 0xe1000
	s_mov_b32 s58, 0xe8000
	s_mov_b32 s59, 0x1e00000
	s_movk_i32 s60, 0x5800
	s_mov_b32 s1, 0
	s_lshl_b32 s100, s2, 3
	s_sub_i32 s100, s101, s100
	s_mul_i32 s8, s2, 40
	s_add_i32 s8, s8, s100
	s_lshl_b32 s9, s8, 1
	s_add_i32 s9, s9, 0x7fffd000
	s_lshl_b32 s15, s8, 5
	s_mov_b32 s100, 0
	s_branch .LBB0_27
.LBB0_26:
	s_add_i32 s100, s100, 1
	s_cmp_lt_u32 s100, 5
	s_cbranch_scc0 .Lcv0_six
	s_add_i32 s8, s8, 8
	s_add_i32 s9, s9, 16
	s_addk_i32 s15, 0x100
	s_branch .LBB0_27
.Lcv0_six:
	s_cmp_eq_u32 s100, 5
	s_cbranch_scc0 .LBB0_43
	s_add_i32 s8, s101, 0x2800
	s_cmpk_lt_i32 s8, 0x2a80
	s_cbranch_scc0 .LBB0_43
	s_lshl_b32 s9, s8, 1
	s_add_i32 s9, s9, 0x7fffd000
	s_lshl_b32 s15, s8, 5
